# phase B load balance: the Toeplitz fill is done only by the 144 workgroups that run 7 GEMM units (grid-stride loop re-based), not by the 112 that run 8
# speedup vs baseline: 1.0041x; 1.0041x over previous
; __device__ __forceinline__ int tid_() { int t = threadIdx.x; asm volatile("" : "+v"(t)); return t; }
; __device__ __forceinline__ int bid_() { int t = blockIdx.x; asm volatile("" : "+s"(t)); return t; }
; __device__ __forceinline__ int nblk_() { int t = gridDim.x; asm volatile("" : "+s"(t)); return t; }
; __device__ __forceinline__ void toeplitz_fill(KArgs& a, int l) {
;     const size_t gt = (size_t)bid_() * 512 + tid_(), gn = (size_t)nblk_() * 512;
;     const float* KT = (const float*)(a.ws + OFF_KTAB); bf16_t* BTY = (bf16_t*)(a.ws + OFF_BTY);
;     const float* dsk = a.s5_d + l * 512;
;     for (size_t e = gt; e < (size_t)32 * 512 * 64; e += gn) {
;         const int k8 = (int)(e & 63), row = (int)((e >> 6) & 511), gI = (int)(e >> 15);
;         const int t = row >> 4, n = row & 15, s = k8 >> 1, m0 = (k8 & 1) * 8;
.LBB0_344:
	s_mov_b32 s22, s84
	s_ashr_i32 s23, s22, 31
	v_mov_b32_e32 v2, v216
	s_lshl_b64 s[0:1], s[22:23], 9
	s_nop 0
	v_ashrrev_i32_e32 v3, 31, v2
	v_lshl_add_u64 v[10:11], s[0:1], 0, v[2:3]
	v_readlane_b32 s0, v237, 2
	v_readlane_b32 s1, v237, 3
	s_load_dwordx2 s[24:25], s[0:1], 0xf0
	s_mov_b64 s[0:1], 0x100000
	v_cmp_gt_u64_e32 vcc, s[0:1], v[10:11]
	s_waitcnt lgkmcnt(0)
	s_cmp_lg_u32 s24, 0x100
	s_cbranch_scc1 .Ltoep_go
	s_sub_i32 s22, s84, 0x70
	s_cmp_lt_i32 s22, 0
	s_cbranch_scc1 .LBB0_367
	s_ashr_i32 s23, s22, 31
	s_lshl_b64 s[0:1], s[22:23], 9
	v_lshl_add_u64 v[10:11], s[0:1], 0, v[2:3]
	s_movk_i32 s24, 0x90
	s_mov_b64 s[0:1], 0x100000
	v_cmp_gt_u64_e32 vcc, s[0:1], v[10:11]
.Ltoep_go:
	s_and_saveexec_b64 s[0:1], vcc
	s_cbranch_execz .LBB0_367
	s_ashr_i32 s25, s24, 31
	s_load_dwordx2 s[16:17], s[14:15], 0x88
	s_lshl_b64 s[8:9], s[24:25], 9
	s_add_u32 s14, s4, 0xef8000
	s_addc_u32 s15, s5, 0
	s_lshl_b32 s2, s2, 9
	s_ashr_i32 s3, s2, 31
	s_lshl_b64 s[2:3], s[2:3], 2
	v_and_b32_e32 v0, 63, v2
	s_waitcnt lgkmcnt(0)
	s_add_u32 s16, s16, s2
	v_lshlrev_b32_e32 v0, 4, v0
	s_addc_u32 s17, s17, s3
	v_lshl_add_u64 v[4:5], s[4:5], 0, v[0:1]
	s_mov_b64 s[2:3], 0xaaf8000
	v_lshlrev_b32_e32 v0, 3, v2
	v_bfe_u32 v18, v2, 1, 5
	v_lshl_add_u64 v[12:13], v[4:5], 0, s[2:3]
	v_lshl_add_u32 v19, s22, 12, v0
	s_lshl_b32 s2, s24, 12
	s_mov_b64 s[4:5], 0
	s_branch .LBB0_348
